# stagger: WGs of batches 2,3 (blockIdx bit2) sleep 3x127x64 cycles before GEMM1 to de-phase memory-bound epilogues from the other half's K-loops
# speedup vs baseline: 1.0044x; 1.0044x over previous
.LBB0_212:
	s_cmp_lt_i32 s68, 3
	s_cselect_b64 s[4:5], -1, 0
	s_and_b64 s[0:1], s[4:5], s[0:1]
	s_andn2_b64 vcc, exec, s[0:1]
	s_ashr_i32 s3, s2, 31
	s_cbranch_vccnz .LBB0_292
	s_bitcmp1_b32 s2, 2
	s_cbranch_scc0 .Lstag_done
	s_movk_i32 s98, 3
.Lstag_loop:
	s_sleep 127
	s_sub_i32 s98, s98, 1
	s_cmp_lg_u32 s98, 0
	s_cbranch_scc1 .Lstag_loop
.Lstag_done:
	s_cmpk_lt_i32 s2, 0x800
	s_cselect_b64 s[0:1], -1, 0
	s_cmpk_gt_i32 s2, 0x7ff
	v_mbcnt_lo_u32_b32 v4, -1, 0
	v_mbcnt_hi_u32_b32 v4, -1, v4
	s_cbranch_scc1 .LBB0_215
	s_lshr_b32 s4, s3, 29
	s_add_i32 s4, s2, s4
	s_and_b32 s5, s4, -8
	s_sub_i32 s5, s2, s5
	s_lshl_b32 s7, s5, 8
	s_ashr_i32 s4, s4, 3
	s_mul_i32 s6, s5, 0x101
	s_cmp_lt_i32 s5, 0
	s_cselect_b32 s5, s6, s7
	s_add_i32 s4, s5, s4
	s_ashr_i32 s5, s4, 31
	s_lshr_b32 s5, s5, 24
	s_add_i32 s5, s4, s5
	s_ashr_i32 s6, s5, 8
	s_and_b32 s5, s5, 0xffffff00
	s_sub_i32 s4, s4, s5
	s_sext_i32_i16 s5, s4
	s_bfe_u32 s5, s5, 0x3001c
	s_add_i32 s5, s4, s5
	s_sext_i32_i16 s7, s5
	s_and_b32 s5, s5, 0xfff8
	s_sub_i32 s4, s4, s5
	s_lshl_b32 s6, s6, 3
	s_sext_i32_i16 s4, s4
	s_add_i32 s76, s6, s4
	s_ashr_i32 s4, s7, 3
	s_and_b32 s5, s4, -4
	s_lshr_b32 s5, 0x41d950c8, s5
	s_and_b32 s5, s5, 28
	s_and_b32 s4, s4, 3
	s_or_b32 s78, s5, s4

	.amdhsa_kernel _Z7hyb_fwd4Args
		.amdhsa_group_segment_fixed_size 0
		.amdhsa_private_segment_fixed_size 0
		.amdhsa_kernarg_size 416
		.amdhsa_user_sgpr_count 2
		.amdhsa_user_sgpr_dispatch_ptr 0
		.amdhsa_user_sgpr_queue_ptr 0
		.amdhsa_user_sgpr_kernarg_segment_ptr 1
		.amdhsa_user_sgpr_dispatch_id 0
		.amdhsa_user_sgpr_kernarg_preload_length 0
		.amdhsa_user_sgpr_kernarg_preload_offset 0
		.amdhsa_user_sgpr_private_segment_size 0
		.amdhsa_uses_dynamic_stack 0
		.amdhsa_enable_private_segment 0
		.amdhsa_system_sgpr_workgroup_id_x 1
		.amdhsa_system_sgpr_workgroup_id_y 0
		.amdhsa_system_sgpr_workgroup_id_z 0
		.amdhsa_system_sgpr_workgroup_info 0
		.amdhsa_system_vgpr_workitem_id 0
		.amdhsa_next_free_vgpr 252
		.amdhsa_next_free_sgpr 100
		.amdhsa_accum_offset 252
		.amdhsa_reserve_vcc 1
		.amdhsa_float_round_mode_32 0
		.amdhsa_float_round_mode_16_64 0
		.amdhsa_float_denorm_mode_32 3
		.amdhsa_float_denorm_mode_16_64 3
		.amdhsa_dx10_clamp 1
		.amdhsa_ieee_mode 1
		.amdhsa_fp16_overflow 0
		.amdhsa_tg_split 0
		.amdhsa_exception_fp_ieee_invalid_op 0
		.amdhsa_exception_fp_denorm_src 0
		.amdhsa_exception_fp_ieee_div_zero 0
		.amdhsa_exception_fp_ieee_overflow 0
		.amdhsa_exception_fp_ieee_underflow 0
		.amdhsa_exception_fp_ieee_inexact 0
		.amdhsa_exception_int_div_zero 0
	.end_amdhsa_kernel
